# odd attention: K/V tiles double-buffered in LDS (second image 43040 B higher, static LDS 78880), next tile written after the last P.V read, one workgroup barrier per tile
# baseline (speedup 1.0000x reference)
.LBB0_425:
	v_mov_b32_e32 v52, v228
	s_mul_i32 s3, s5, 0x1800
	v_ashrrev_i32_e32 v16, 31, v52
	v_lshrrev_b32_e32 v16, 28, v16
	v_add_u32_e32 v16, v52, v16
	v_ashrrev_i32_e32 v124, 4, v16
	v_and_b32_e32 v56, -16, v16
	v_add_u32_e32 v16, 0x100, v52
	v_ashrrev_i32_e32 v17, 31, v16
	s_mul_hi_u32 s16, s4, 0x1800
	v_lshrrev_b32_e32 v17, 28, v17
	v_add_u32_e32 v18, 0x300, v52
	s_add_i32 s16, s16, s3
	s_mul_i32 s3, s4, 0x1800
	v_add_u32_e32 v17, v16, v17
	v_ashrrev_i32_e32 v19, 31, v18
	s_add_u32 s3, s44, s3
	v_and_b32_e32 v58, -16, v17
	v_lshrrev_b32_e32 v19, 28, v19
	s_addc_u32 s17, s45, s16
	s_lshl_b64 s[12:13], s[12:13], 1
	v_sub_u32_e32 v59, v16, v58
	v_add_u32_e32 v16, 0x200, v52
	v_add_u32_e32 v19, v18, v19
	s_add_u32 s16, s3, s12
	v_ashrrev_i32_e32 v126, 4, v17
	v_ashrrev_i32_e32 v17, 31, v16
	v_and_b32_e32 v62, -16, v19
	s_addc_u32 s17, s17, s13
	v_lshrrev_b32_e32 v17, 28, v17
	v_ashrrev_i32_e32 v130, 4, v19
	v_sub_u32_e32 v63, v18, v62
	v_mov_b64_e32 v[0:1], s[16:17]
	v_lshlrev_b32_e32 v26, 3, v59
	v_add_u32_e32 v17, v16, v17
	v_lshlrev_b32_e32 v18, 3, v63
	v_mad_i64_i32 v[20:21], s[16:17], s10, v130, 0
	v_mad_i64_i32 v[32:33], s[16:17], s10, v126, 0
	v_ashrrev_i32_e32 v27, 31, v26
	v_and_b32_e32 v60, -16, v17
	v_ashrrev_i32_e32 v19, 31, v18
	v_lshlrev_b64 v[28:29], 1, v[20:21]
	v_lshlrev_b64 v[48:49], 1, v[32:33]
	v_sub_u32_e32 v57, v52, v56
	v_ashrrev_i32_e32 v128, 4, v17
	v_sub_u32_e32 v61, v16, v60
	v_lshl_add_u64 v[20:21], s[8:9], 0, v[28:29]
	v_lshlrev_b64 v[132:133], 1, v[18:19]
	v_lshl_add_u64 v[32:33], s[8:9], 0, v[48:49]
	v_lshlrev_b64 v[136:137], 1, v[26:27]
	v_ashrrev_i32_e32 v53, 6, v52
	v_and_b32_e32 v55, 15, v52
	v_lshlrev_b32_e32 v24, 3, v57
	v_lshlrev_b32_e32 v16, 3, v61
	v_lshl_add_u64 v[18:19], v[20:21], 0, v[132:133]
	v_mad_i64_i32 v[20:21], s[16:17], s10, v128, 0
	v_lshl_add_u64 v[26:27], v[32:33], 0, v[136:137]
	v_mad_i64_i32 v[32:33], s[16:17], s10, v124, 0
	v_bfe_u32 v54, v52, 4, 2
	v_lshl_or_b32 v122, v53, 4, v55
	v_ashrrev_i32_e32 v25, 31, v24
	v_ashrrev_i32_e32 v17, 31, v16
	v_lshlrev_b64 v[30:31], 1, v[20:21]
	v_lshlrev_b64 v[50:51], 1, v[32:33]
	v_mad_i64_i32 v[0:1], s[16:17], v122, s28, v[0:1]
	v_lshlrev_b32_e32 v196, 4, v54
	v_lshl_add_u64 v[20:21], s[8:9], 0, v[30:31]
	v_lshlrev_b64 v[134:135], 1, v[16:17]
	v_lshl_add_u64 v[32:33], s[8:9], 0, v[50:51]
	v_lshlrev_b64 v[138:139], 1, v[24:25]
	v_lshl_add_u64 v[12:13], v[0:1], 0, v[196:197]
	v_lshl_add_u64 v[16:17], v[20:21], 0, v[134:135]
	v_lshl_add_u64 v[24:25], v[32:33], 0, v[138:139]
	global_load_dwordx4 v[0:3], v[12:13], off
	global_load_dwordx4 v[4:7], v[12:13], off offset:64
	global_load_dwordx4 v[8:11], v[12:13], off offset:128
	s_nop 0
	global_load_dwordx4 v[12:15], v[12:13], off offset:192
	s_nop 0
	global_load_dwordx4 v[20:23], v[18:19], off
	s_nop 0
	global_load_dwordx4 v[16:19], v[16:17], off
	s_nop 0
	global_load_dwordx4 v[36:39], v[26:27], off
	global_load_dwordx4 v[32:35], v[24:25], off
	v_lshl_add_u64 v[24:25], s[6:7], 0, v[28:29]
	v_lshl_add_u64 v[26:27], s[6:7], 0, v[30:31]
	v_lshl_add_u64 v[24:25], v[24:25], 0, v[132:133]
	v_lshl_add_u64 v[26:27], v[26:27], 0, v[134:135]
	global_load_dwordx4 v[44:47], v[24:25], off
	global_load_dwordx4 v[40:43], v[26:27], off
	v_lshl_add_u64 v[24:25], s[6:7], 0, v[48:49]
	v_lshl_add_u64 v[26:27], s[6:7], 0, v[50:51]
	v_lshl_add_u64 v[24:25], v[24:25], 0, v[136:137]
	v_lshl_add_u64 v[26:27], v[26:27], 0, v[138:139]
	global_load_dwordx4 v[28:31], v[24:25], off
	s_nop 0
	global_load_dwordx4 v[24:27], v[26:27], off
	s_add_u32 s3, s44, s14
	s_addc_u32 s14, s45, s15
	s_add_u32 s3, s3, s12
	s_addc_u32 s17, s14, s13
	v_lshlrev_b32_e32 v120, 3, v54
	v_bfe_u32 v50, v52, 2, 2
	s_movk_i32 s19, 0x120
	s_add_u32 s14, s3, 0x800
	v_lshl_or_b32 v48, v53, 5, v55
	v_or_b32_e32 v50, v120, v50
	v_lshlrev_b32_e32 v51, 3, v52
	v_mul_lo_u32 v129, v124, s19
	v_mul_lo_u32 v141, v126, s19
	v_mul_lo_u32 v143, v128, s19
	v_mul_lo_u32 v145, v130, s19
	s_movk_i32 s19, 0xa0
	s_addc_u32 s15, s17, 0
	v_sub_u32_e32 v49, v196, v120
	v_and_b32_e32 v51, 24, v51
	v_lshlrev_b32_e32 v140, 4, v57
	v_lshlrev_b32_e32 v142, 4, v59
	v_lshlrev_b32_e32 v144, 4, v61
	v_lshlrev_b32_e32 v146, 4, v63
	v_sub_u32_e32 v52, v129, v56
	v_sub_u32_e32 v53, v141, v58
	v_sub_u32_e32 v54, v143, v60
	v_sub_u32_e32 v56, v145, v62
	v_mul_u32_u24_e32 v55, 0x120, v55
	v_mul_lo_u32 v48, v48, s19
	v_mul_u32_u24_e32 v50, 0x110, v50
	v_mov_b32_e32 v104, v197
	v_mov_b32_e32 v105, v197
	v_mov_b32_e32 v106, v197
	v_mov_b32_e32 v107, v197
	s_add_u32 s16, s3, 0x1000
	v_add_u32_e32 v147, v52, v140
	v_add_u32_e32 v148, v53, v142
	v_add_u32_e32 v149, v54, v144
	v_add_u32_e32 v150, v56, v146
	v_add_u32_e32 v151, v196, v48
	v_add_u32_e32 v152, v51, v50
	v_add_u32_e32 v153, v196, v55
	v_add_u32_e32 v154, v49, v48
	v_mov_b64_e32 v[60:61], v[104:105]
	v_mov_b64_e32 v[72:73], v[104:105]
	v_mov_b64_e32 v[64:65], v[104:105]
	v_mov_b64_e32 v[48:49], v[104:105]
	v_mov_b64_e32 v[56:57], v[104:105]
	v_mov_b64_e32 v[88:89], v[104:105]
	v_mov_b64_e32 v[92:93], v[104:105]
	v_mov_b64_e32 v[110:111], v[106:107]
	v_mov_b64_e32 v[76:77], v[104:105]
	v_mov_b64_e32 v[84:85], v[104:105]
	v_mov_b64_e32 v[80:81], v[104:105]
	v_mov_b64_e32 v[52:53], v[104:105]
	v_mov_b64_e32 v[68:69], v[104:105]
	v_mov_b64_e32 v[100:101], v[104:105]
	v_mov_b64_e32 v[96:97], v[104:105]
	s_addc_u32 s17, s17, 0
	v_ashrrev_i32_e32 v123, 31, v122
	s_or_b32 s3, s18, s2
	s_sub_i32 s25, 1, s2
	s_add_i32 s26, s18, s2
	s_mov_b32 s28, 0
	v_mov_b32_e32 v155, 0xf149f2ca
	v_mov_b32_e32 v131, 0
	v_mov_b64_e32 v[62:63], v[106:107]
	v_mov_b64_e32 v[74:75], v[106:107]
	v_mov_b64_e32 v[66:67], v[106:107]
	v_mov_b64_e32 v[50:51], v[106:107]
	v_mov_b64_e32 v[58:59], v[106:107]
	v_mov_b64_e32 v[90:91], v[106:107]
	v_mov_b64_e32 v[94:95], v[106:107]
	v_mov_b64_e32 v[108:109], v[104:105]
	v_mov_b64_e32 v[78:79], v[106:107]
	v_mov_b64_e32 v[86:87], v[106:107]
	v_mov_b64_e32 v[82:83], v[106:107]
	v_mov_b64_e32 v[54:55], v[106:107]
	v_mov_b64_e32 v[70:71], v[106:107]
	v_mov_b64_e32 v[102:103], v[106:107]
	v_mov_b64_e32 v[98:99], v[106:107]
	v_mov_b32_e32 v121, 0
	v_mov_b32_e32 v156, 0xf149f2ca
	v_mul_lo_u32 v242, v124, s10
	v_mul_lo_u32 v243, v126, s10
	v_mul_lo_u32 v244, v128, s10
	v_mul_lo_u32 v245, v130, s10
	s_movk_i32 s34, 0xc00
	v_mul_lo_u32 v246, v124, s34
	v_mul_lo_u32 v247, v126, s34
	v_mul_lo_u32 v248, v128, s34
	v_mul_lo_u32 v249, v130, s34
	v_lshl_add_u32 v242, v242, 1, v138
	v_lshl_add_u32 v243, v243, 1, v136
	v_lshl_add_u32 v244, v244, 1, v134
	v_lshl_add_u32 v245, v245, 1, v132
	v_lshl_add_u32 v246, v246, 1, v138
	v_lshl_add_u32 v247, v247, 1, v136
	v_lshl_add_u32 v248, v248, 1, v134
	v_lshl_add_u32 v249, v249, 1, v132
	v_add_u32_e32 v238, v129, v140
	v_add_u32_e32 v239, v141, v142
	v_add_u32_e32 v240, v143, v144
	v_add_u32_e32 v241, v145, v146
	v_bfe_u32 v214, v228, 4, 2
	v_mul_u32_u24_e32 v214, 0x440, v214
	v_sub_u32_e32 v214, v152, v214
	s_mov_b32 s72, 43040
	s_mov_b32 s32, 0x3e38aa3b
	s_barrier
	s_waitcnt vmcnt(0)
	ds_write_b128 v238, v[24:27]
	ds_write_b128 v239, v[28:31]
	s_add_i32 s27, s28, 1
	ds_write_b128 v240, v[40:43]
	s_cmp_ge_u32 s27, s3
	ds_write_b128 v241, v[44:47]
	ds_write_b128 v147, v[32:35] offset:18432
	ds_write_b128 v148, v[36:39] offset:18432
	ds_write_b128 v149, v[16:19] offset:18432
	ds_write_b128 v150, v[20:23] offset:18432
	s_waitcnt lgkmcnt(0)
	s_barrier
	s_cbranch_scc1 .Ldb_p430
	s_cmp_lt_u32 s27, s2
	s_mov_b32 s29, s27
	s_mov_b64 s[18:19], s[10:11]
	s_mov_b64 s[22:23], s[6:7]
	s_mov_b64 s[20:21], s[8:9]
	s_cbranch_scc1 .Ldb_429p
	s_add_i32 s29, s25, s28
	s_mov_b64 s[18:19], 0xc00
	s_mov_b64 s[22:23], s[14:15]
	s_mov_b64 s[20:21], s[16:17]

.Ldb_p430:
	s_mov_b32 s28, 0
	v_add_u32_e32 v238, s72, v238
	v_add_u32_e32 v239, s72, v239
	v_add_u32_e32 v240, s72, v240
	v_add_u32_e32 v241, s72, v241
	v_add_u32_e32 v147, s72, v147
	v_add_u32_e32 v148, s72, v148
	v_add_u32_e32 v149, s72, v149
	v_add_u32_e32 v150, s72, v150
.LBB0_426:
	s_mov_b32 s32, 0x3e38aa3b
	s_add_i32 s27, s28, 1
	ds_read_b128 v[198:201], v153
	ds_read_b128 v[202:205], v153 offset:4608
	ds_read_b128 v[206:209], v153 offset:9216
	ds_read_b128 v[210:213], v153 offset:13824
	ds_read_b128 v[216:219], v153 offset:64
	ds_read_b128 v[220:223], v153 offset:4672
	ds_read_b128 v[224:227], v153 offset:9280
	ds_read_b128 v[230:233], v153 offset:13888
	s_waitcnt lgkmcnt(7)
	v_mfma_f32_16x16x32_bf16 v[174:177], v[198:201], v[0:3], 0
	ds_read_b128 v[198:201], v153 offset:128
	s_waitcnt lgkmcnt(7)
	v_mfma_f32_16x16x32_bf16 v[160:163], v[202:205], v[0:3], 0
	ds_read_b128 v[202:205], v153 offset:4736
	s_waitcnt lgkmcnt(7)
	v_mfma_f32_16x16x32_bf16 v[166:169], v[206:209], v[0:3], 0
	ds_read_b128 v[206:209], v153 offset:9344
	s_waitcnt lgkmcnt(7)
	v_mfma_f32_16x16x32_bf16 v[170:173], v[210:213], v[0:3], 0
	ds_read_b128 v[210:213], v153 offset:13952
	s_waitcnt lgkmcnt(7)
	v_mfma_f32_16x16x32_bf16 v[174:177], v[216:219], v[4:7], v[174:177]
	ds_read_b128 v[216:219], v153 offset:192
	s_waitcnt lgkmcnt(7)
	v_mfma_f32_16x16x32_bf16 v[160:163], v[220:223], v[4:7], v[160:163]
	ds_read_b128 v[220:223], v153 offset:4800
	s_waitcnt lgkmcnt(7)
	v_mfma_f32_16x16x32_bf16 v[166:169], v[224:227], v[4:7], v[166:169]
	ds_read_b128 v[224:227], v153 offset:9408
	s_waitcnt lgkmcnt(7)
	v_mfma_f32_16x16x32_bf16 v[170:173], v[230:233], v[4:7], v[170:173]
	ds_read_b128 v[230:233], v153 offset:14016
	s_waitcnt lgkmcnt(7)
	v_mfma_f32_16x16x32_bf16 v[112:115], v[198:201], v[8:11], 0
	s_waitcnt lgkmcnt(6)
	v_mfma_f32_16x16x32_bf16 v[116:119], v[202:205], v[8:11], 0
	s_waitcnt lgkmcnt(5)
	v_mfma_f32_16x16x32_bf16 v[186:189], v[206:209], v[8:11], 0
	s_waitcnt lgkmcnt(4)
	v_mfma_f32_16x16x32_bf16 v[182:185], v[210:213], v[8:11], 0
	s_waitcnt lgkmcnt(3)
	v_mfma_f32_16x16x32_bf16 v[112:115], v[216:219], v[12:15], v[112:115]
	s_waitcnt lgkmcnt(2)
	v_mfma_f32_16x16x32_bf16 v[116:119], v[220:223], v[12:15], v[116:119]
	s_waitcnt lgkmcnt(1)
	v_mfma_f32_16x16x32_bf16 v[186:189], v[224:227], v[12:15], v[186:189]
	s_waitcnt lgkmcnt(0)
	v_mfma_f32_16x16x32_bf16 v[182:185], v[230:233], v[12:15], v[182:185]
	v_max3_f32 v194, v174, s30, v175
	v_max3_f32 v194, v194, v176, v177
	v_max3_f32 v194, v194, v160, v161
	v_max3_f32 v194, v194, v162, v163
	v_max3_f32 v194, v194, v166, v167
	v_max3_f32 v194, v194, v168, v169
	v_max3_f32 v194, v194, v170, v171
	v_max3_f32 v194, v194, v172, v173
	v_mov_b32_e32 v195, v194
	s_nop 1
	v_permlane16_swap_b32_e32 v194, v195
	v_max_f32_e32 v194, v194, v195
	v_mov_b32_e32 v195, v194
	s_nop 1
	v_permlane32_swap_b32_e32 v194, v195
	v_max_f32_e32 v194, v194, v195
	v_mul_f32_e32 v194, 0x3e38aa3b, v194
	v_max_f32_e32 v194, v155, v194
	v_pk_fma_f32 v[174:175], v[174:175], s[32:33], v[194:195] op_sel_hi:[1,0,0] neg_lo:[0,0,1] neg_hi:[0,0,1]
	v_pk_fma_f32 v[176:177], v[176:177], s[32:33], v[194:195] op_sel_hi:[1,0,0] neg_lo:[0,0,1] neg_hi:[0,0,1]
	v_pk_fma_f32 v[160:161], v[160:161], s[32:33], v[194:195] op_sel_hi:[1,0,0] neg_lo:[0,0,1] neg_hi:[0,0,1]
	v_pk_fma_f32 v[162:163], v[162:163], s[32:33], v[194:195] op_sel_hi:[1,0,0] neg_lo:[0,0,1] neg_hi:[0,0,1]
	v_pk_fma_f32 v[166:167], v[166:167], s[32:33], v[194:195] op_sel_hi:[1,0,0] neg_lo:[0,0,1] neg_hi:[0,0,1]
	v_pk_fma_f32 v[168:169], v[168:169], s[32:33], v[194:195] op_sel_hi:[1,0,0] neg_lo:[0,0,1] neg_hi:[0,0,1]
	v_pk_fma_f32 v[170:171], v[170:171], s[32:33], v[194:195] op_sel_hi:[1,0,0] neg_lo:[0,0,1] neg_hi:[0,0,1]
	v_pk_fma_f32 v[172:173], v[172:173], s[32:33], v[194:195] op_sel_hi:[1,0,0] neg_lo:[0,0,1] neg_hi:[0,0,1]
	v_cmp_gt_f32_e32 vcc, v194, v155
	s_cbranch_vccz .LBB0_432
	v_sub_f32_e32 v155, v155, v194
	v_exp_f32_e32 v215, v155
	v_mov_b32_e32 v155, v194
	v_mul_f32_e32 v131, v131, v215
	v_pk_mul_f32 v[98:99], v[98:99], v[214:215] op_sel:[0,1] op_sel_hi:[1,1]
	v_pk_mul_f32 v[96:97], v[96:97], v[214:215] op_sel:[0,1] op_sel_hi:[1,1]
	v_pk_mul_f32 v[102:103], v[102:103], v[214:215] op_sel:[0,1] op_sel_hi:[1,1]
	v_pk_mul_f32 v[100:101], v[100:101], v[214:215] op_sel:[0,1] op_sel_hi:[1,1]
	v_pk_mul_f32 v[70:71], v[70:71], v[214:215] op_sel:[0,1] op_sel_hi:[1,1]
	v_pk_mul_f32 v[68:69], v[68:69], v[214:215] op_sel:[0,1] op_sel_hi:[1,1]
	v_pk_mul_f32 v[54:55], v[54:55], v[214:215] op_sel:[0,1] op_sel_hi:[1,1]
	v_pk_mul_f32 v[52:53], v[52:53], v[214:215] op_sel:[0,1] op_sel_hi:[1,1]
	v_pk_mul_f32 v[82:83], v[82:83], v[214:215] op_sel:[0,1] op_sel_hi:[1,1]
	v_pk_mul_f32 v[80:81], v[80:81], v[214:215] op_sel:[0,1] op_sel_hi:[1,1]
	v_pk_mul_f32 v[86:87], v[86:87], v[214:215] op_sel:[0,1] op_sel_hi:[1,1]
	v_pk_mul_f32 v[84:85], v[84:85], v[214:215] op_sel:[0,1] op_sel_hi:[1,1]
	v_pk_mul_f32 v[78:79], v[78:79], v[214:215] op_sel:[0,1] op_sel_hi:[1,1]
	v_pk_mul_f32 v[76:77], v[76:77], v[214:215] op_sel:[0,1] op_sel_hi:[1,1]
	v_pk_mul_f32 v[110:111], v[110:111], v[214:215] op_sel:[0,1] op_sel_hi:[1,1]
	v_pk_mul_f32 v[108:109], v[108:109], v[214:215] op_sel:[0,1] op_sel_hi:[1,1]

.LBB0_434:
	v_exp_f32_e32 v112, v112
	v_exp_f32_e32 v113, v113
	v_exp_f32_e32 v114, v114
	v_exp_f32_e32 v115, v115
	v_exp_f32_e32 v116, v116
	v_exp_f32_e32 v117, v117
	v_exp_f32_e32 v118, v118
	v_exp_f32_e32 v119, v119
	v_exp_f32_e32 v186, v186
	v_exp_f32_e32 v187, v187
	v_exp_f32_e32 v188, v188
	v_exp_f32_e32 v189, v189
	v_exp_f32_e32 v182, v182
	v_exp_f32_e32 v183, v183
	v_exp_f32_e32 v184, v184
	v_exp_f32_e32 v185, v185
	s_nop 0
	v_cvt_pk_bf16_f32 v224, v112, v113
	v_cvt_pk_bf16_f32 v226, v116, v117
	v_cvt_pk_bf16_f32 v230, v186, v187
	v_cvt_pk_bf16_f32 v232, v182, v183
	v_pk_add_f32 v[112:113], v[112:113], v[114:115]
	v_pk_add_f32 v[116:117], v[116:117], v[118:119]
	v_pk_add_f32 v[186:187], v[186:187], v[188:189]
	v_pk_add_f32 v[182:183], v[182:183], v[184:185]
	v_pk_add_f32 v[112:113], v[112:113], v[116:117]
	v_pk_add_f32 v[182:183], v[182:183], v[186:187]
	v_cvt_pk_bf16_f32 v225, v114, v115
	v_pk_add_f32 v[182:183], v[182:183], v[112:113]
	v_cvt_pk_bf16_f32 v227, v118, v119
	v_add_f32_e32 v182, v182, v183
	v_cvt_pk_bf16_f32 v231, v188, v189
	v_add_f32_e32 v121, v182, v121
	v_cvt_pk_bf16_f32 v233, v184, v185
	ds_read_b64_tr_b16 v[198:199], v214 offset:18432
	ds_read_b64_tr_b16 v[200:201], v214 offset:22784
	ds_read_b64_tr_b16 v[202:203], v214 offset:18464
	ds_read_b64_tr_b16 v[204:205], v214 offset:22816
	ds_read_b64_tr_b16 v[206:207], v214 offset:18496
	ds_read_b64_tr_b16 v[208:209], v214 offset:22848
	ds_read_b64_tr_b16 v[210:211], v214 offset:18528
	ds_read_b64_tr_b16 v[212:213], v214 offset:22880
	s_waitcnt lgkmcnt(6)
	v_mfma_f32_16x16x32_bf16 v[96:99], v[198:201], v[216:219], v[96:99]
	v_mfma_f32_16x16x32_bf16 v[92:95], v[198:201], v[224:227], v[92:95]
	ds_read_b64_tr_b16 v[198:199], v214 offset:18560
	ds_read_b64_tr_b16 v[200:201], v214 offset:22912
	s_waitcnt lgkmcnt(6)
	v_mfma_f32_16x16x32_bf16 v[100:103], v[202:205], v[216:219], v[100:103]
	v_mfma_f32_16x16x32_bf16 v[88:91], v[202:205], v[224:227], v[88:91]
	ds_read_b64_tr_b16 v[202:203], v214 offset:18592
	ds_read_b64_tr_b16 v[204:205], v214 offset:22944
	s_waitcnt lgkmcnt(6)
	v_mfma_f32_16x16x32_bf16 v[68:71], v[206:209], v[216:219], v[68:71]
	v_mfma_f32_16x16x32_bf16 v[56:59], v[206:209], v[224:227], v[56:59]
	ds_read_b64_tr_b16 v[206:207], v214 offset:18624
	ds_read_b64_tr_b16 v[208:209], v214 offset:22976
	s_waitcnt lgkmcnt(6)
	v_mfma_f32_16x16x32_bf16 v[52:55], v[210:213], v[216:219], v[52:55]
	v_mfma_f32_16x16x32_bf16 v[48:51], v[210:213], v[224:227], v[48:51]
	ds_read_b64_tr_b16 v[210:211], v214 offset:18656
	ds_read_b64_tr_b16 v[212:213], v214 offset:23008
	s_waitcnt lgkmcnt(6)
	v_mfma_f32_16x16x32_bf16 v[80:83], v[198:201], v[216:219], v[80:83]
	v_mfma_f32_16x16x32_bf16 v[64:67], v[198:201], v[224:227], v[64:67]
	ds_read_b64_tr_b16 v[198:199], v214 offset:27136
	ds_read_b64_tr_b16 v[200:201], v214 offset:31488
	s_waitcnt lgkmcnt(6)
	v_mfma_f32_16x16x32_bf16 v[84:87], v[202:205], v[216:219], v[84:87]
	v_mfma_f32_16x16x32_bf16 v[72:75], v[202:205], v[224:227], v[72:75]
	ds_read_b64_tr_b16 v[202:203], v214 offset:27168
	ds_read_b64_tr_b16 v[204:205], v214 offset:31520
	s_waitcnt lgkmcnt(6)
	v_mfma_f32_16x16x32_bf16 v[76:79], v[206:209], v[216:219], v[76:79]
	v_mfma_f32_16x16x32_bf16 v[60:63], v[206:209], v[224:227], v[60:63]
	ds_read_b64_tr_b16 v[206:207], v214 offset:27200
	ds_read_b64_tr_b16 v[208:209], v214 offset:31552
	s_waitcnt lgkmcnt(6)
	v_mfma_f32_16x16x32_bf16 v[108:111], v[210:213], v[216:219], v[108:111]
	v_mfma_f32_16x16x32_bf16 v[104:107], v[210:213], v[224:227], v[104:107]
	ds_read_b64_tr_b16 v[210:211], v214 offset:27232
	ds_read_b64_tr_b16 v[212:213], v214 offset:31584
	s_waitcnt lgkmcnt(6)
	v_mfma_f32_16x16x32_bf16 v[96:99], v[198:201], v[220:223], v[96:99]
	v_mfma_f32_16x16x32_bf16 v[92:95], v[198:201], v[230:233], v[92:95]
	ds_read_b64_tr_b16 v[198:199], v214 offset:27264
	ds_read_b64_tr_b16 v[200:201], v214 offset:31616
	s_waitcnt lgkmcnt(6)
	v_mfma_f32_16x16x32_bf16 v[100:103], v[202:205], v[220:223], v[100:103]
	v_mfma_f32_16x16x32_bf16 v[88:91], v[202:205], v[230:233], v[88:91]
	ds_read_b64_tr_b16 v[202:203], v214 offset:27296
	ds_read_b64_tr_b16 v[204:205], v214 offset:31648
	s_waitcnt lgkmcnt(6)
	v_mfma_f32_16x16x32_bf16 v[68:71], v[206:209], v[220:223], v[68:71]
	v_mfma_f32_16x16x32_bf16 v[56:59], v[206:209], v[230:233], v[56:59]
	ds_read_b64_tr_b16 v[206:207], v214 offset:27328
	ds_read_b64_tr_b16 v[208:209], v214 offset:31680
	s_waitcnt lgkmcnt(6)
	v_mfma_f32_16x16x32_bf16 v[52:55], v[210:213], v[220:223], v[52:55]
	v_mfma_f32_16x16x32_bf16 v[48:51], v[210:213], v[230:233], v[48:51]
	ds_read_b64_tr_b16 v[210:211], v214 offset:27360
	ds_read_b64_tr_b16 v[212:213], v214 offset:31712
	s_cmp_ge_u32 s27, s3
	s_cbranch_scc1 .Ldb_nowrite
	s_waitcnt vmcnt(0)
	ds_write_b128 v238, v[24:27]
	ds_write_b128 v239, v[28:31]
	ds_write_b128 v240, v[40:43]
	ds_write_b128 v241, v[44:47]
	ds_write_b128 v147, v[32:35] offset:18432
	ds_write_b128 v148, v[36:39] offset:18432
	ds_write_b128 v149, v[16:19] offset:18432
	ds_write_b128 v150, v[20:23] offset:18432
	s_add_i32 s73, s27, 1
	s_add_i32 s74, s28, 1
	s_cmp_ge_u32 s73, s3
	s_cbranch_scc1 .Ldb_noload
	s_cmp_lt_u32 s73, s2
	s_mov_b32 s29, s73
	s_mov_b64 s[18:19], s[10:11]
	s_mov_b64 s[22:23], s[6:7]
	s_mov_b64 s[20:21], s[8:9]
	s_cbranch_scc1 .Ldb_429l
	s_add_i32 s29, s25, s74
	s_mov_b64 s[18:19], 0xc00
	s_mov_b64 s[22:23], s[14:15]
	s_mov_b64 s[20:21], s[16:17]

.Ldb_noload:
	s_waitcnt lgkmcnt(14)
	v_mfma_f32_16x16x32_bf16 v[80:83], v[198:201], v[220:223], v[80:83]
	v_mfma_f32_16x16x32_bf16 v[64:67], v[198:201], v[230:233], v[64:67]
	s_waitcnt lgkmcnt(12)
	v_mfma_f32_16x16x32_bf16 v[84:87], v[202:205], v[220:223], v[84:87]
	v_mfma_f32_16x16x32_bf16 v[72:75], v[202:205], v[230:233], v[72:75]
	s_waitcnt lgkmcnt(10)
	v_mfma_f32_16x16x32_bf16 v[76:79], v[206:209], v[220:223], v[76:79]
	v_mfma_f32_16x16x32_bf16 v[60:63], v[206:209], v[230:233], v[60:63]
	s_waitcnt lgkmcnt(8)
	v_mfma_f32_16x16x32_bf16 v[108:111], v[210:213], v[220:223], v[108:111]
	v_mfma_f32_16x16x32_bf16 v[104:107], v[210:213], v[230:233], v[104:107]
	s_branch .Ldb_join
.Ldb_nowrite:
	s_waitcnt lgkmcnt(6)
	v_mfma_f32_16x16x32_bf16 v[80:83], v[198:201], v[220:223], v[80:83]
	v_mfma_f32_16x16x32_bf16 v[64:67], v[198:201], v[230:233], v[64:67]
	s_waitcnt lgkmcnt(4)
	v_mfma_f32_16x16x32_bf16 v[84:87], v[202:205], v[220:223], v[84:87]
	v_mfma_f32_16x16x32_bf16 v[72:75], v[202:205], v[230:233], v[72:75]
	s_waitcnt lgkmcnt(2)
	v_mfma_f32_16x16x32_bf16 v[76:79], v[206:209], v[220:223], v[76:79]
	v_mfma_f32_16x16x32_bf16 v[60:63], v[206:209], v[230:233], v[60:63]
	s_waitcnt lgkmcnt(0)
	v_mfma_f32_16x16x32_bf16 v[108:111], v[210:213], v[220:223], v[108:111]
	v_mfma_f32_16x16x32_bf16 v[104:107], v[210:213], v[230:233], v[104:107]
.Ldb_join:
	s_waitcnt lgkmcnt(0)
	s_barrier
	v_add_u32_e32 v153, s72, v153
	v_add_u32_e32 v214, s72, v214
	v_subrev_u32_e32 v238, s72, v238
	v_subrev_u32_e32 v239, s72, v239
	v_subrev_u32_e32 v240, s72, v240
	v_subrev_u32_e32 v241, s72, v241
	v_subrev_u32_e32 v147, s72, v147
	v_subrev_u32_e32 v148, s72, v148
	v_subrev_u32_e32 v149, s72, v149
	v_subrev_u32_e32 v150, s72, v150
	s_sub_i32 s72, 0, s72
	s_cmp_lg_u32 s26, s27
	s_cbranch_scc0 .LBB0_419
	s_mov_b32 s28, s27
	s_branch .LBB0_426

	.amdhsa_kernel _Z14fwd_megakernel1P
		.amdhsa_group_segment_fixed_size 78880
		.amdhsa_private_segment_fixed_size 0
		.amdhsa_kernarg_size 560
		.amdhsa_user_sgpr_count 2
		.amdhsa_user_sgpr_dispatch_ptr 0
		.amdhsa_user_sgpr_queue_ptr 0
		.amdhsa_user_sgpr_kernarg_segment_ptr 1
		.amdhsa_user_sgpr_dispatch_id 0
		.amdhsa_user_sgpr_kernarg_preload_length 0
		.amdhsa_user_sgpr_kernarg_preload_offset 0
		.amdhsa_user_sgpr_private_segment_size 0
		.amdhsa_uses_dynamic_stack 0
		.amdhsa_enable_private_segment 0
		.amdhsa_system_sgpr_workgroup_id_x 1
		.amdhsa_system_sgpr_workgroup_id_y 0
		.amdhsa_system_sgpr_workgroup_id_z 0
		.amdhsa_system_sgpr_workgroup_info 0
		.amdhsa_system_vgpr_workitem_id 2
		.amdhsa_next_free_vgpr 256
		.amdhsa_next_free_sgpr 102
		.amdhsa_accum_offset 256
		.amdhsa_reserve_vcc 1
		.amdhsa_float_round_mode_32 0
		.amdhsa_float_round_mode_16_64 0
		.amdhsa_float_denorm_mode_32 3
		.amdhsa_float_denorm_mode_16_64 3
		.amdhsa_dx10_clamp 1
		.amdhsa_ieee_mode 1
		.amdhsa_fp16_overflow 0
		.amdhsa_tg_split 0
		.amdhsa_exception_fp_ieee_invalid_op 0
		.amdhsa_exception_fp_denorm_src 0
		.amdhsa_exception_fp_ieee_div_zero 0
		.amdhsa_exception_fp_ieee_overflow 0
		.amdhsa_exception_fp_ieee_underflow 0
		.amdhsa_exception_fp_ieee_inexact 0
		.amdhsa_exception_int_div_zero 0
	.end_amdhsa_kernel

amdhsa.kernels:
  - .agpr_count:     0
    .args:
      - .offset:         0
        .size:           304
        .value_kind:     by_value
      - .offset:         304
        .size:           4
        .value_kind:     hidden_block_count_x
      - .offset:         308
        .size:           4
        .value_kind:     hidden_block_count_y
      - .offset:         312
        .size:           4
        .value_kind:     hidden_block_count_z
      - .offset:         316
        .size:           2
        .value_kind:     hidden_group_size_x
      - .offset:         318
        .size:           2
        .value_kind:     hidden_group_size_y
      - .offset:         320
        .size:           2
        .value_kind:     hidden_group_size_z
      - .offset:         322
        .size:           2
        .value_kind:     hidden_remainder_x
      - .offset:         324
        .size:           2
        .value_kind:     hidden_remainder_y
      - .offset:         326
        .size:           2
        .value_kind:     hidden_remainder_z
      - .offset:         344
        .size:           8
        .value_kind:     hidden_global_offset_x
      - .offset:         352
        .size:           8
        .value_kind:     hidden_global_offset_y
      - .offset:         360
        .size:           8
        .value_kind:     hidden_global_offset_z
      - .offset:         368
        .size:           2
        .value_kind:     hidden_grid_dims
      - .offset:         392
        .size:           8
        .value_kind:     hidden_multigrid_sync_arg
    .group_segment_fixed_size: 78880
    .kernarg_segment_align: 8
    .kernarg_segment_size: 560
    .language:       OpenCL C
    .language_version:
      - 2
      - 0
    .max_flat_workgroup_size: 256
    .name:           _Z14fwd_megakernel1P
    .private_segment_fixed_size: 0
    .sgpr_count:     108
    .sgpr_spill_count: 204
    .symbol:         _Z14fwd_megakernel1P.kd
    .uniform_work_group_size: 1
    .uses_dynamic_stack: false
    .vgpr_count:     256
    .vgpr_spill_count: 0
    .wavefront_size: 64
